# P2/P8: first K iteration of every unit peeled, its first MFMA per accumulator uses an inline-zero C operand; the 128 accumulator-clearing moves per unit are gone
# speedup vs baseline: 1.0020x; 1.0020x over previous
; #define PG8_STAGE(bufoff, gbase, voff) do { _Pragma("unroll") for (int _i = 0; _i < 2; ++_i) \
;         __builtin_amdgcn_global_load_lds((const unsigned*)((const char*)(gbase) + (voff)[_i]), (PG8_LAS unsigned*)(lds + (bufoff) + ldsw + _i * 8192), 16, 0, 0); } while (0)
; #define PG8_LDA(dst, b, h) do { _Pragma("unroll") for (int m = 0; m < 4; ++m) _Pragma("unroll") for (int k = 0; k < 2; ++k) dst[m][k] = *(const PG8_LAS bf16x8*)(lds + PG8_SA(b, h) + aoff + m * 2048 + k * 1024); } while (0)
; #define PG8_LDB(dst, b, h) do { _Pragma("unroll") for (int n = 0; n < 2; ++n) _Pragma("unroll") for (int k = 0; k < 2; ++k) dst[n][k] = *(const PG8_LAS bf16x8*)(lds + PG8_SB(b, h) + boff + n * 2048 + k * 1024); } while (0)
; #define PG8_MMA(ai, bj, At, Bt) do { __builtin_amdgcn_s_setprio(1); _Pragma("unroll") for (int m = 0; m < 4; ++m) _Pragma("unroll") for (int n = 0; n < 2; ++n) _Pragma("unroll") for (int k = 0; k < 2; ++k) \
;         acc[ai][bj][m][n] = __builtin_amdgcn_mfma_f32_16x16x32_bf16(Bt[n][k], At[m][k], acc[ai][bj][m][n], 0, 0, 0); __builtin_amdgcn_s_setprio(0); } while (0)
; #define PG8_WAIT_V(n) asm volatile("s_waitcnt vmcnt(" #n ")" ::: "memory")
; #define PG8_WAIT_L(n) asm volatile("s_waitcnt lgkmcnt(" #n ")" ::: "memory")
; #define PG8_BAR __builtin_amdgcn_s_barrier()
; #define PG8_SCHED __builtin_amdgcn_sched_barrier(0)
; template <class Epi, class Sched, bool ALIGN_EPI = false, bool SP2 = false>
; __device__ __forceinline__ void gemm_phase(PG8_LAS unsigned char* lds, const Gemm g, const Sched& S, const Epi& E) {
;     ...
;             PG8_LDB(B0, 0, 0); PG8_LDB(B1, 0, 1); PG8_SCHED; PG8_LDA(At, 0, 0); PG8_STAGE(PG8_SA(1, 1), a1 + hstep, voffA);
;             PG8_WAIT_V(8); PG8_WAIT_L(0); PG8_BAR; PG8_MMA(0, 0, At, B0); PG8_MMA(0, 1, At, B1); PG8_BAR; PG8_SCHED;
;             PG8_LDA(At, 0, 1); PG8_STAGE(PG8_SB(0, 0), b2, voffB); PG8_STAGE(PG8_SB(0, 1), b2 + hstep, voffB); PG8_STAGE(PG8_SA(0, 0), a2, voffA);
;             PG8_WAIT_V(8); PG8_WAIT_L(0); PG8_BAR; PG8_MMA(1, 0, At, B0); PG8_MMA(1, 1, At, B1); PG8_BAR; PG8_SCHED;
.LBB0_269:
	s_ashr_i32 s81, s80, 31
	s_lshl_b64 s[0:1], s[80:81], 19
	s_add_u32 s82, s76, s0
	s_addc_u32 s83, s77, s1
	s_and_b64 s[0:1], s[4:5], exec
	s_cselect_b32 s0, s83, s89
	s_cselect_b32 s1, s82, s88
	s_ashr_i32 s69, s68, 31
	s_lshl_b64 s[84:85], s[68:69], 19
	s_add_u32 s84, s8, s84
	s_addc_u32 s85, s9, s85
	s_and_b64 s[92:93], s[4:5], exec
	s_cselect_b32 s7, s85, s91
	s_cselect_b32 s69, s84, s90
	s_add_u32 s88, s88, 0x40080
	s_addc_u32 s89, s89, 0
	s_add_u32 s81, s90, 0x100
	s_addc_u32 s87, s91, 0
	s_mov_b32 s96, -2
	ds_read_b128 v[146:149], v152
	ds_read_b128 v[156:159], v152 offset:1024
	ds_read_b128 v[160:163], v152 offset:2048
	ds_read_b128 v[164:167], v152 offset:3072
	ds_read_b128 v[168:171], v153
	ds_read_b128 v[172:175], v153 offset:1024
	ds_read_b128 v[176:179], v153 offset:2048
	ds_read_b128 v[180:183], v153 offset:3072
	s_add_u32 s3, s88, 0xfffc0080
	s_addc_u32 s90, s89, -1
	s_cmp_eq_u32 s96, 12
	s_cselect_b32 s93, s0, s90
	s_cselect_b32 s92, s1, s3
	s_cselect_b32 s91, s7, s87
	s_cselect_b32 s90, s69, s81
	v_lshl_add_u64 v[216:217], s[88:89], 0, v[138:139]
	s_add_i32 m0, s13, 0xc000
	ds_read_b128 v[184:187], v154
	ds_read_b128 v[188:191], v154 offset:1024
	ds_read_b128 v[192:195], v154 offset:2048
	ds_read_b128 v[196:199], v154 offset:3072
	ds_read_b128 v[200:203], v154 offset:4096
	ds_read_b128 v[204:207], v154 offset:5120
	ds_read_b128 v[208:211], v154 offset:6144
	ds_read_b128 v[212:215], v154 offset:7168
	global_load_lds_dwordx4 v[216:217], off
	v_lshl_add_u64 v[216:217], s[88:89], 0, v[140:141]
	s_add_i32 m0, s13, 0xe000
	s_nop 0
	global_load_lds_dwordx4 v[216:217], off
	s_waitcnt vmcnt(8)
	s_waitcnt lgkmcnt(0)
	s_barrier
	s_setprio 1
	s_waitcnt lgkmcnt(0)
	v_mfma_f32_16x16x32_bf16 v[126:129], v[146:149], v[184:187], 0
	v_mfma_f32_16x16x32_bf16 v[122:125], v[160:163], v[184:187], 0
	v_mfma_f32_16x16x32_bf16 v[118:121], v[146:149], v[192:195], 0
	v_mfma_f32_16x16x32_bf16 v[114:117], v[160:163], v[192:195], 0
	v_mfma_f32_16x16x32_bf16 v[110:113], v[146:149], v[200:203], 0
	v_mfma_f32_16x16x32_bf16 v[106:109], v[160:163], v[200:203], 0
	v_mfma_f32_16x16x32_bf16 v[102:105], v[146:149], v[208:211], 0
	v_mfma_f32_16x16x32_bf16 v[98:101], v[160:163], v[208:211], 0
	v_mfma_f32_16x16x32_bf16 v[126:129], v[156:159], v[188:191], v[126:129]
	v_mfma_f32_16x16x32_bf16 v[122:125], v[164:167], v[188:191], v[122:125]
	v_mfma_f32_16x16x32_bf16 v[118:121], v[156:159], v[196:199], v[118:121]
	v_mfma_f32_16x16x32_bf16 v[114:117], v[164:167], v[196:199], v[114:117]
	v_mfma_f32_16x16x32_bf16 v[110:113], v[156:159], v[204:207], v[110:113]
	v_mfma_f32_16x16x32_bf16 v[106:109], v[164:167], v[204:207], v[106:109]
	v_mfma_f32_16x16x32_bf16 v[102:105], v[156:159], v[212:215], v[102:105]
	v_mfma_f32_16x16x32_bf16 v[98:101], v[164:167], v[212:215], v[98:101]
	s_setprio 0
	s_setprio 1
	v_mfma_f32_16x16x32_bf16 v[62:65], v[168:171], v[184:187], 0
	v_mfma_f32_16x16x32_bf16 v[58:61], v[176:179], v[184:187], 0
	v_mfma_f32_16x16x32_bf16 v[54:57], v[168:171], v[192:195], 0
	v_mfma_f32_16x16x32_bf16 v[50:53], v[176:179], v[192:195], 0
	v_mfma_f32_16x16x32_bf16 v[46:49], v[168:171], v[200:203], 0
	v_mfma_f32_16x16x32_bf16 v[42:45], v[176:179], v[200:203], 0
	v_mfma_f32_16x16x32_bf16 v[38:41], v[168:171], v[208:211], 0
	v_mfma_f32_16x16x32_bf16 v[34:37], v[176:179], v[208:211], 0
	v_mfma_f32_16x16x32_bf16 v[62:65], v[172:175], v[188:191], v[62:65]
	v_mfma_f32_16x16x32_bf16 v[58:61], v[180:183], v[188:191], v[58:61]
	v_mfma_f32_16x16x32_bf16 v[54:57], v[172:175], v[196:199], v[54:57]
	v_mfma_f32_16x16x32_bf16 v[50:53], v[180:183], v[196:199], v[50:53]
	v_mfma_f32_16x16x32_bf16 v[46:49], v[172:175], v[204:207], v[46:49]
	v_mfma_f32_16x16x32_bf16 v[42:45], v[180:183], v[204:207], v[42:45]
	v_mfma_f32_16x16x32_bf16 v[38:41], v[172:175], v[212:215], v[38:41]
	v_mfma_f32_16x16x32_bf16 v[34:37], v[180:183], v[212:215], v[34:37]
	s_setprio 0
	s_barrier
	s_add_i32 s3, s33, s12
	v_lshl_add_u64 v[216:217], s[90:91], 0, v[132:133]
	s_mov_b32 m0, s3
	ds_read_b128 v[184:187], v154 offset:16384
	ds_read_b128 v[188:191], v154 offset:17408
	ds_read_b128 v[192:195], v154 offset:18432
	ds_read_b128 v[196:199], v154 offset:19456
	ds_read_b128 v[200:203], v154 offset:20480
	ds_read_b128 v[204:207], v154 offset:21504
	ds_read_b128 v[208:211], v154 offset:22528
	ds_read_b128 v[212:215], v154 offset:23552
	global_load_lds_dwordx4 v[216:217], off
	s_add_i32 m0, s3, 0x2000
	s_add_u32 vcc_lo, s90, 0x40000
	v_lshl_add_u64 v[218:219], s[90:91], 0, v[136:137]
	s_addc_u32 vcc_hi, s91, 0
	s_add_i32 s3, s75, s12
	global_load_lds_dwordx4 v[218:219], off
	v_lshl_add_u64 v[220:221], vcc, 0, v[132:133]
	s_mov_b32 m0, s3
	v_lshl_add_u64 v[222:223], s[92:93], 0, v[134:135]
	global_load_lds_dwordx4 v[220:221], off
	v_lshl_add_u64 v[220:221], vcc, 0, v[136:137]
	s_add_i32 m0, s3, 0x2000
	s_nop 0
	global_load_lds_dwordx4 v[220:221], off
	v_lshl_add_u64 v[220:221], s[92:93], 0, v[130:131]
	s_mov_b32 m0, s13
	s_nop 0
	global_load_lds_dwordx4 v[220:221], off
	s_mov_b32 m0, s34
	s_nop 0
	global_load_lds_dwordx4 v[222:223], off
	s_waitcnt vmcnt(8)
	s_waitcnt lgkmcnt(0)
	s_barrier
; #define PG8_STAGE(bufoff, gbase, voff) do { _Pragma("unroll") for (int _i = 0; _i < 2; ++_i) \
;         __builtin_amdgcn_global_load_lds((const unsigned*)((const char*)(gbase) + (voff)[_i]), (PG8_LAS unsigned*)(lds + (bufoff) + ldsw + _i * 8192), 16, 0, 0); } while (0)
; #define PG8_LDA(dst, b, h) do { _Pragma("unroll") for (int m = 0; m < 4; ++m) _Pragma("unroll") for (int k = 0; k < 2; ++k) dst[m][k] = *(const PG8_LAS bf16x8*)(lds + PG8_SA(b, h) + aoff + m * 2048 + k * 1024); } while (0)
; #define PG8_LDB(dst, b, h) do { _Pragma("unroll") for (int n = 0; n < 2; ++n) _Pragma("unroll") for (int k = 0; k < 2; ++k) dst[n][k] = *(const PG8_LAS bf16x8*)(lds + PG8_SB(b, h) + boff + n * 2048 + k * 1024); } while (0)
; #define PG8_MMA(ai, bj, At, Bt) do { __builtin_amdgcn_s_setprio(1); _Pragma("unroll") for (int m = 0; m < 4; ++m) _Pragma("unroll") for (int n = 0; n < 2; ++n) _Pragma("unroll") for (int k = 0; k < 2; ++k) \
;         acc[ai][bj][m][n] = __builtin_amdgcn_mfma_f32_16x16x32_bf16(Bt[n][k], At[m][k], acc[ai][bj][m][n], 0, 0, 0); __builtin_amdgcn_s_setprio(0); } while (0)
; #define PG8_WAIT_V(n) asm volatile("s_waitcnt vmcnt(" #n ")" ::: "memory")
; #define PG8_WAIT_L(n) asm volatile("s_waitcnt lgkmcnt(" #n ")" ::: "memory")
; #define PG8_BAR __builtin_amdgcn_s_barrier()
; #define PG8_SCHED __builtin_amdgcn_sched_barrier(0)
; template <class Epi, class Sched, bool ALIGN_EPI = false, bool SP2 = false>
; __device__ __forceinline__ void gemm_phase(PG8_LAS unsigned char* lds, const Gemm g, const Sched& S, const Epi& E) {
;     ...
;             PG8_WAIT_V(8); PG8_WAIT_L(0); PG8_BAR; PG8_MMA(1, 0, At, B0); PG8_MMA(1, 1, At, B1); PG8_BAR; PG8_SCHED;
;             PG8_LDB(B0, 1, 0); PG8_LDB(B1, 1, 1); PG8_SCHED; PG8_LDA(At, 1, 0); PG8_STAGE(PG8_SA(0, 1), a2 + hstep, voffA);
;             PG8_WAIT_V(8); PG8_WAIT_L(0); PG8_BAR; PG8_MMA(0, 0, At, B0); PG8_MMA(0, 1, At, B1); PG8_BAR; PG8_SCHED;
	s_setprio 1
	s_waitcnt lgkmcnt(0)
	v_mfma_f32_16x16x32_bf16 v[94:97], v[146:149], v[184:187], 0
	v_mfma_f32_16x16x32_bf16 v[90:93], v[160:163], v[184:187], 0
	v_mfma_f32_16x16x32_bf16 v[86:89], v[146:149], v[192:195], 0
	v_mfma_f32_16x16x32_bf16 v[82:85], v[160:163], v[192:195], 0
	v_mfma_f32_16x16x32_bf16 v[78:81], v[146:149], v[200:203], 0
	v_mfma_f32_16x16x32_bf16 v[74:77], v[160:163], v[200:203], 0
	v_mfma_f32_16x16x32_bf16 v[70:73], v[146:149], v[208:211], 0
	v_mfma_f32_16x16x32_bf16 v[66:69], v[160:163], v[208:211], 0
	v_mfma_f32_16x16x32_bf16 v[94:97], v[156:159], v[188:191], v[94:97]
	v_mfma_f32_16x16x32_bf16 v[90:93], v[164:167], v[188:191], v[90:93]
	v_mfma_f32_16x16x32_bf16 v[86:89], v[156:159], v[196:199], v[86:89]
	v_mfma_f32_16x16x32_bf16 v[82:85], v[164:167], v[196:199], v[82:85]
	v_mfma_f32_16x16x32_bf16 v[78:81], v[156:159], v[204:207], v[78:81]
	v_mfma_f32_16x16x32_bf16 v[74:77], v[164:167], v[204:207], v[74:77]
	v_mfma_f32_16x16x32_bf16 v[70:73], v[156:159], v[212:215], v[70:73]
	v_mfma_f32_16x16x32_bf16 v[66:69], v[164:167], v[212:215], v[66:69]
	s_setprio 0
	s_setprio 1
	v_mfma_f32_16x16x32_bf16 v[30:33], v[168:171], v[184:187], 0
	v_mfma_f32_16x16x32_bf16 v[26:29], v[176:179], v[184:187], 0
	v_mfma_f32_16x16x32_bf16 v[22:25], v[168:171], v[192:195], 0
	v_mfma_f32_16x16x32_bf16 v[18:21], v[176:179], v[192:195], 0
	v_mfma_f32_16x16x32_bf16 v[14:17], v[168:171], v[200:203], 0
	v_mfma_f32_16x16x32_bf16 v[10:13], v[176:179], v[200:203], 0
	v_mfma_f32_16x16x32_bf16 v[6:9], v[168:171], v[208:211], 0
	v_mfma_f32_16x16x32_bf16 v[2:5], v[176:179], v[208:211], 0
	v_mfma_f32_16x16x32_bf16 v[30:33], v[172:175], v[188:191], v[30:33]
	v_mfma_f32_16x16x32_bf16 v[26:29], v[180:183], v[188:191], v[26:29]
	v_mfma_f32_16x16x32_bf16 v[22:25], v[172:175], v[196:199], v[22:25]
	v_mfma_f32_16x16x32_bf16 v[18:21], v[180:183], v[196:199], v[18:21]
	v_mfma_f32_16x16x32_bf16 v[14:17], v[172:175], v[204:207], v[14:17]
	v_mfma_f32_16x16x32_bf16 v[10:13], v[180:183], v[204:207], v[10:13]
	v_mfma_f32_16x16x32_bf16 v[6:9], v[172:175], v[212:215], v[6:9]
	v_mfma_f32_16x16x32_bf16 v[2:5], v[180:183], v[212:215], v[2:5]
	s_setprio 0
	s_barrier
	s_add_i32 s3, 0, 0x18000
	s_add_i32 s97, 0, 0x1c000
	v_add_u32_e32 v164, s3, v150
	v_add_u32_e32 v180, s97, v150
	ds_read_b128 v[146:149], v164
	ds_read_b128 v[156:159], v164 offset:1024
	ds_read_b128 v[160:163], v164 offset:2048
	ds_read_b128 v[164:167], v164 offset:3072
	ds_read_b128 v[168:171], v180
	ds_read_b128 v[172:175], v180 offset:1024
	ds_read_b128 v[176:179], v180 offset:2048
	ds_read_b128 v[180:183], v180 offset:3072
	s_add_u32 s92, s92, 0x40000
	s_addc_u32 s93, s93, 0
	s_mov_b32 m0, s35
	v_lshl_add_u64 v[224:225], s[92:93], 0, v[130:131]
	ds_read_b128 v[184:187], v154 offset:32768
	ds_read_b128 v[188:191], v154 offset:33792
	ds_read_b128 v[192:195], v154 offset:34816
	ds_read_b128 v[196:199], v154 offset:35840
	ds_read_b128 v[200:203], v154 offset:36864
	ds_read_b128 v[204:207], v154 offset:37888
	ds_read_b128 v[208:211], v154 offset:38912
	ds_read_b128 v[212:215], v154 offset:39936
	global_load_lds_dwordx4 v[224:225], off
	v_lshl_add_u64 v[224:225], s[92:93], 0, v[134:135]
	s_mov_b32 m0, s70
	s_nop 0
	global_load_lds_dwordx4 v[224:225], off
	s_waitcnt vmcnt(8)
	s_waitcnt lgkmcnt(0)
	s_barrier
	s_setprio 1
	s_waitcnt lgkmcnt(0)
	v_mfma_f32_16x16x32_bf16 v[126:129], v[146:149], v[184:187], v[126:129]
	v_mfma_f32_16x16x32_bf16 v[122:125], v[160:163], v[184:187], v[122:125]
	v_mfma_f32_16x16x32_bf16 v[118:121], v[146:149], v[192:195], v[118:121]
	v_mfma_f32_16x16x32_bf16 v[114:117], v[160:163], v[192:195], v[114:117]
	v_mfma_f32_16x16x32_bf16 v[110:113], v[146:149], v[200:203], v[110:113]
	v_mfma_f32_16x16x32_bf16 v[106:109], v[160:163], v[200:203], v[106:109]
	v_mfma_f32_16x16x32_bf16 v[102:105], v[146:149], v[208:211], v[102:105]
	v_mfma_f32_16x16x32_bf16 v[98:101], v[160:163], v[208:211], v[98:101]
	v_mfma_f32_16x16x32_bf16 v[126:129], v[156:159], v[188:191], v[126:129]
	v_mfma_f32_16x16x32_bf16 v[122:125], v[164:167], v[188:191], v[122:125]
	v_mfma_f32_16x16x32_bf16 v[118:121], v[156:159], v[196:199], v[118:121]
	v_mfma_f32_16x16x32_bf16 v[114:117], v[164:167], v[196:199], v[114:117]
	v_mfma_f32_16x16x32_bf16 v[110:113], v[156:159], v[204:207], v[110:113]
	v_mfma_f32_16x16x32_bf16 v[106:109], v[164:167], v[204:207], v[106:109]
	v_mfma_f32_16x16x32_bf16 v[102:105], v[156:159], v[212:215], v[102:105]
	v_mfma_f32_16x16x32_bf16 v[98:101], v[164:167], v[212:215], v[98:101]
	s_setprio 0
	s_setprio 1
	v_mfma_f32_16x16x32_bf16 v[62:65], v[168:171], v[184:187], v[62:65]
	v_mfma_f32_16x16x32_bf16 v[58:61], v[176:179], v[184:187], v[58:61]
	v_mfma_f32_16x16x32_bf16 v[54:57], v[168:171], v[192:195], v[54:57]
	v_mfma_f32_16x16x32_bf16 v[50:53], v[176:179], v[192:195], v[50:53]
	v_mfma_f32_16x16x32_bf16 v[46:49], v[168:171], v[200:203], v[46:49]
	v_mfma_f32_16x16x32_bf16 v[42:45], v[176:179], v[200:203], v[42:45]
	v_mfma_f32_16x16x32_bf16 v[38:41], v[168:171], v[208:211], v[38:41]
	v_mfma_f32_16x16x32_bf16 v[34:37], v[176:179], v[208:211], v[34:37]
	v_mfma_f32_16x16x32_bf16 v[62:65], v[172:175], v[188:191], v[62:65]
	v_mfma_f32_16x16x32_bf16 v[58:61], v[180:183], v[188:191], v[58:61]
	v_mfma_f32_16x16x32_bf16 v[54:57], v[172:175], v[196:199], v[54:57]
	v_mfma_f32_16x16x32_bf16 v[50:53], v[180:183], v[196:199], v[50:53]
	v_mfma_f32_16x16x32_bf16 v[46:49], v[172:175], v[204:207], v[46:49]
	v_mfma_f32_16x16x32_bf16 v[42:45], v[180:183], v[204:207], v[42:45]
	v_mfma_f32_16x16x32_bf16 v[38:41], v[172:175], v[212:215], v[38:41]
	v_mfma_f32_16x16x32_bf16 v[34:37], v[180:183], v[212:215], v[34:37]
	s_setprio 0
	s_barrier
; #define PG8_STAGE(bufoff, gbase, voff) do { _Pragma("unroll") for (int _i = 0; _i < 2; ++_i) \
;         __builtin_amdgcn_global_load_lds((const unsigned*)((const char*)(gbase) + (voff)[_i]), (PG8_LAS unsigned*)(lds + (bufoff) + ldsw + _i * 8192), 16, 0, 0); } while (0)
; #define PG8_LDA(dst, b, h) do { _Pragma("unroll") for (int m = 0; m < 4; ++m) _Pragma("unroll") for (int k = 0; k < 2; ++k) dst[m][k] = *(const PG8_LAS bf16x8*)(lds + PG8_SA(b, h) + aoff + m * 2048 + k * 1024); } while (0)
; #define PG8_MMA(ai, bj, At, Bt) do { __builtin_amdgcn_s_setprio(1); _Pragma("unroll") for (int m = 0; m < 4; ++m) _Pragma("unroll") for (int n = 0; n < 2; ++n) _Pragma("unroll") for (int k = 0; k < 2; ++k) \
;         acc[ai][bj][m][n] = __builtin_amdgcn_mfma_f32_16x16x32_bf16(Bt[n][k], At[m][k], acc[ai][bj][m][n], 0, 0, 0); __builtin_amdgcn_s_setprio(0); } while (0)
; #define PG8_WAIT_V(n) asm volatile("s_waitcnt vmcnt(" #n ")" ::: "memory")
; #define PG8_WAIT_L(n) asm volatile("s_waitcnt lgkmcnt(" #n ")" ::: "memory")
; #define PG8_BAR __builtin_amdgcn_s_barrier()
; #define PG8_SCHED __builtin_amdgcn_sched_barrier(0)
; template <class Epi, class Sched, bool ALIGN_EPI = false, bool SP2 = false>
; __device__ __forceinline__ void gemm_phase(PG8_LAS unsigned char* lds, const Gemm g, const Sched& S, const Epi& E) {
;     ...
;             PG8_LDA(At, 1, 1); PG8_STAGE(PG8_SB(1, 0), b3, voffB); PG8_STAGE(PG8_SB(1, 1), b3 + hstep, voffB); PG8_STAGE(PG8_SA(1, 0), a3, voffA);
;             PG8_WAIT_V(8); PG8_WAIT_L(0); PG8_BAR; PG8_MMA(1, 0, At, B0); PG8_MMA(1, 1, At, B1); PG8_BAR; PG8_SCHED;
	s_add_i32 s3, s3, s12
	v_lshl_add_u64 v[216:217], v[216:217], 0, s[28:29]
	s_mov_b32 m0, s3
	ds_read_b128 v[184:187], v154 offset:49152
	ds_read_b128 v[188:191], v154 offset:50176
	ds_read_b128 v[192:195], v154 offset:51200
	ds_read_b128 v[196:199], v154 offset:52224
	ds_read_b128 v[200:203], v154 offset:53248
	ds_read_b128 v[204:207], v154 offset:54272
	ds_read_b128 v[208:211], v154 offset:55296
	ds_read_b128 v[212:215], v154 offset:56320
	global_load_lds_dwordx4 v[216:217], off
	s_add_i32 m0, s3, 0x2000
	s_add_u32 s90, s90, 0x40080
	v_lshl_add_u64 v[216:217], v[218:219], 0, s[28:29]
	s_addc_u32 s91, s91, 0
	s_add_i32 s3, s97, s12
	global_load_lds_dwordx4 v[216:217], off
	v_lshl_add_u64 v[216:217], s[90:91], 0, v[132:133]
	s_mov_b32 m0, s3
	s_nop 0
	global_load_lds_dwordx4 v[216:217], off
	v_lshl_add_u64 v[216:217], s[90:91], 0, v[136:137]
	s_add_i32 m0, s3, 0x2000
	s_nop 0
	global_load_lds_dwordx4 v[216:217], off
	v_lshl_add_u64 v[216:217], v[220:221], 0, s[28:29]
	s_mov_b32 m0, s71
	s_nop 0
	global_load_lds_dwordx4 v[216:217], off
	v_lshl_add_u64 v[216:217], v[222:223], 0, s[28:29]
	s_mov_b32 m0, s72
	s_nop 0
	global_load_lds_dwordx4 v[216:217], off
	s_waitcnt vmcnt(8)
	s_waitcnt lgkmcnt(0)
	s_barrier
	s_setprio 1
	s_waitcnt lgkmcnt(0)
	v_mfma_f32_16x16x32_bf16 v[94:97], v[146:149], v[184:187], v[94:97]
	s_add_i32 s96, s96, 2
	s_add_u32 s88, s88, 0x100
	s_addc_u32 s89, s89, 0
	s_add_u32 s81, s81, 0x100
	s_addc_u32 s87, s87, 0
	s_cmp_gt_u32 s96, 13
	v_mfma_f32_16x16x32_bf16 v[90:93], v[160:163], v[184:187], v[90:93]
	v_mfma_f32_16x16x32_bf16 v[86:89], v[146:149], v[192:195], v[86:89]
	v_mfma_f32_16x16x32_bf16 v[82:85], v[160:163], v[192:195], v[82:85]
	v_mfma_f32_16x16x32_bf16 v[78:81], v[146:149], v[200:203], v[78:81]
	v_mfma_f32_16x16x32_bf16 v[74:77], v[160:163], v[200:203], v[74:77]
	v_mfma_f32_16x16x32_bf16 v[70:73], v[146:149], v[208:211], v[70:73]
	v_mfma_f32_16x16x32_bf16 v[66:69], v[160:163], v[208:211], v[66:69]
	v_mfma_f32_16x16x32_bf16 v[94:97], v[156:159], v[188:191], v[94:97]
	v_mfma_f32_16x16x32_bf16 v[90:93], v[164:167], v[188:191], v[90:93]
	v_mfma_f32_16x16x32_bf16 v[86:89], v[156:159], v[196:199], v[86:89]
	v_mfma_f32_16x16x32_bf16 v[82:85], v[164:167], v[196:199], v[82:85]
	v_mfma_f32_16x16x32_bf16 v[78:81], v[156:159], v[204:207], v[78:81]
	v_mfma_f32_16x16x32_bf16 v[74:77], v[164:167], v[204:207], v[74:77]
	v_mfma_f32_16x16x32_bf16 v[70:73], v[156:159], v[212:215], v[70:73]
	v_mfma_f32_16x16x32_bf16 v[66:69], v[164:167], v[212:215], v[66:69]
	s_setprio 0
	s_setprio 1
	v_mfma_f32_16x16x32_bf16 v[30:33], v[168:171], v[184:187], v[30:33]
	v_mfma_f32_16x16x32_bf16 v[26:29], v[176:179], v[184:187], v[26:29]
	v_mfma_f32_16x16x32_bf16 v[22:25], v[168:171], v[192:195], v[22:25]
	v_mfma_f32_16x16x32_bf16 v[18:21], v[176:179], v[192:195], v[18:21]
	v_mfma_f32_16x16x32_bf16 v[14:17], v[168:171], v[200:203], v[14:17]
	v_mfma_f32_16x16x32_bf16 v[10:13], v[176:179], v[200:203], v[10:13]
	v_mfma_f32_16x16x32_bf16 v[6:9], v[168:171], v[208:211], v[6:9]
	v_mfma_f32_16x16x32_bf16 v[2:5], v[176:179], v[208:211], v[2:5]
	v_mfma_f32_16x16x32_bf16 v[30:33], v[172:175], v[188:191], v[30:33]
	v_mfma_f32_16x16x32_bf16 v[26:29], v[180:183], v[188:191], v[26:29]
	v_mfma_f32_16x16x32_bf16 v[22:25], v[172:175], v[196:199], v[22:25]
	v_mfma_f32_16x16x32_bf16 v[18:21], v[180:183], v[196:199], v[18:21]
	v_mfma_f32_16x16x32_bf16 v[14:17], v[172:175], v[204:207], v[14:17]
	v_mfma_f32_16x16x32_bf16 v[10:13], v[180:183], v[204:207], v[10:13]
	v_mfma_f32_16x16x32_bf16 v[6:9], v[172:175], v[212:215], v[6:9]
	v_mfma_f32_16x16x32_bf16 v[2:5], v[180:183], v[212:215], v[2:5]
	s_setprio 0
	s_barrier

; #define PG8_STAGE(bufoff, gbase, voff) do { _Pragma("unroll") for (int _i = 0; _i < 2; ++_i) \
;         __builtin_amdgcn_global_load_lds((const unsigned*)((const char*)(gbase) + (voff)[_i]), (PG8_LAS unsigned*)(lds + (bufoff) + ldsw + _i * 8192), 16, 0, 0); } while (0)
; #define PG8_LDA(dst, b, h) do { _Pragma("unroll") for (int m = 0; m < 4; ++m) _Pragma("unroll") for (int k = 0; k < 2; ++k) dst[m][k] = *(const PG8_LAS bf16x8*)(lds + PG8_SA(b, h) + aoff + m * 2048 + k * 1024); } while (0)
; #define PG8_LDB(dst, b, h) do { _Pragma("unroll") for (int n = 0; n < 2; ++n) _Pragma("unroll") for (int k = 0; k < 2; ++k) dst[n][k] = *(const PG8_LAS bf16x8*)(lds + PG8_SB(b, h) + boff + n * 2048 + k * 1024); } while (0)
; #define PG8_WAIT_V(n) asm volatile("s_waitcnt vmcnt(" #n ")" ::: "memory")
; #define PG8_WAIT_L(n) asm volatile("s_waitcnt lgkmcnt(" #n ")" ::: "memory")
; #define PG8_BAR __builtin_amdgcn_s_barrier()
; #define PG8_SCHED __builtin_amdgcn_sched_barrier(0)
; template <class Epi, class Sched, bool ALIGN_EPI = false, bool SP2 = false>
; __device__ __forceinline__ void gemm_phase(PG8_LAS unsigned char* lds, const Gemm g, const Sched& S, const Epi& E) {
;     ...
;         const bool has_next = S.next(ui + 1, nxt);
;         const char* nA = has_next ? (const char*)g.A + (size_t)nxt.pm * tstep : cA; const char* nB = has_next ? (const char*)g.Bt + (size_t)nxt.pn * tstep : cB;
;         for (int t = 0; t < nt; t += 2) {
;             const bool last = (t == nt - 2);
;             const char* a1 = cA + (size_t)(t + 1) * kstep;
;             const char* a2 = last ? nA : cA + (size_t)(t + 2) * kstep; const char* b2 = last ? nB : cB + (size_t)(t + 2) * kstep;
;             const char* a3 = a2 + kstep; const char* b3 = b2 + kstep;
;             if (last && has_next) S.a_ready(nxt);
;             if constexpr (SP2) {
;             PG8_LDB(B0, 0, 0); PG8_LDB(B1, 0, 1); PG8_SCHED; PG8_LDA(At, 0, 0); PG8_STAGE(PG8_SA(1, 1), a1 + hstep, voffA);
;             PG8_WAIT_V(8); PG8_WAIT_L(0); PG8_BAR; PG8_MMA(0, 0, At, B0); PG8_MMA(0, 1, At, B1); PG8_BAR; PG8_SCHED;
;             PG8_LDA(At, 0, 1); PG8_STAGE(PG8_SB(0, 0), b2, voffB); PG8_STAGE(PG8_SB(0, 1), b2 + hstep, voffB); PG8_STAGE(PG8_SA(0, 0), a2, voffA);
;             PG8_WAIT_V(8); PG8_WAIT_L(0); PG8_BAR; PG8_MMA(1, 0, At, B0); PG8_MMA(1, 1, At, B1); PG8_BAR; PG8_SCHED;
.LBB0_1174:
	s_ashr_i32 s27, s26, 31
	s_lshl_b64 s[0:1], s[26:27], 19
	s_add_u32 s30, s20, s0
	s_addc_u32 s31, s21, s1
	s_and_b64 s[0:1], s[4:5], exec
	s_cselect_b32 s0, s31, s41
	s_cselect_b32 s1, s30, s40
	s_ashr_i32 s29, s28, 31
	s_lshl_b64 s[36:37], s[28:29], 19
	s_add_u32 s36, s24, s36
	s_addc_u32 s37, s25, s37
	s_and_b64 s[44:45], s[4:5], exec
	s_cselect_b32 s27, s37, s43
	s_cselect_b32 s29, s36, s42
	s_add_u32 s40, s40, 0x40080
	s_addc_u32 s41, s41, 0
	s_add_u32 s53, s42, 0x100
	s_addc_u32 s54, s43, 0
	s_mov_b32 s55, -2
	ds_read_b128 v[152:155], v148
	ds_read_b128 v[156:159], v148 offset:1024
	ds_read_b128 v[160:163], v148 offset:2048
	ds_read_b128 v[164:167], v148 offset:3072
	ds_read_b128 v[168:171], v149
	ds_read_b128 v[172:175], v149 offset:1024
	ds_read_b128 v[176:179], v149 offset:2048
	ds_read_b128 v[180:183], v149 offset:3072
	s_add_u32 s3, s40, 0xfffc0080
	s_addc_u32 s42, s41, -1
	s_cmp_eq_u32 s55, 12
	s_cselect_b32 s45, s0, s42
	s_cselect_b32 s44, s1, s3
	s_cselect_b32 s43, s27, s54
	s_cselect_b32 s42, s29, s53
	v_lshl_add_u64 v[216:217], s[40:41], 0, v[138:139]
	s_add_i32 m0, s35, 0xc000
	ds_read_b128 v[184:187], v150
	ds_read_b128 v[188:191], v150 offset:1024
	ds_read_b128 v[192:195], v150 offset:2048
	ds_read_b128 v[196:199], v150 offset:3072
	ds_read_b128 v[200:203], v150 offset:4096
	ds_read_b128 v[204:207], v150 offset:5120
	ds_read_b128 v[208:211], v150 offset:6144
	ds_read_b128 v[212:215], v150 offset:7168
	global_load_lds_dwordx4 v[216:217], off
	v_lshl_add_u64 v[216:217], s[40:41], 0, v[140:141]
	s_add_i32 m0, s35, 0xe000
	s_nop 0
	global_load_lds_dwordx4 v[216:217], off
	s_waitcnt vmcnt(8)
	s_waitcnt lgkmcnt(0)
	s_barrier
	s_setprio 1
	s_waitcnt lgkmcnt(0)
	v_mfma_f32_16x16x32_bf16 v[126:129], v[152:155], v[184:187], 0
	v_mfma_f32_16x16x32_bf16 v[122:125], v[160:163], v[184:187], 0
	v_mfma_f32_16x16x32_bf16 v[110:113], v[152:155], v[192:195], 0
	v_mfma_f32_16x16x32_bf16 v[106:109], v[160:163], v[192:195], 0
	v_mfma_f32_16x16x32_bf16 v[94:97], v[152:155], v[200:203], 0
	v_mfma_f32_16x16x32_bf16 v[90:93], v[160:163], v[200:203], 0
	v_mfma_f32_16x16x32_bf16 v[78:81], v[152:155], v[208:211], 0
	v_mfma_f32_16x16x32_bf16 v[74:77], v[160:163], v[208:211], 0
	v_mfma_f32_16x16x32_bf16 v[126:129], v[156:159], v[188:191], v[126:129]
	v_mfma_f32_16x16x32_bf16 v[122:125], v[164:167], v[188:191], v[122:125]
	v_mfma_f32_16x16x32_bf16 v[110:113], v[156:159], v[196:199], v[110:113]
	v_mfma_f32_16x16x32_bf16 v[106:109], v[164:167], v[196:199], v[106:109]
	v_mfma_f32_16x16x32_bf16 v[94:97], v[156:159], v[204:207], v[94:97]
	v_mfma_f32_16x16x32_bf16 v[90:93], v[164:167], v[204:207], v[90:93]
	v_mfma_f32_16x16x32_bf16 v[78:81], v[156:159], v[212:215], v[78:81]
	v_mfma_f32_16x16x32_bf16 v[74:77], v[164:167], v[212:215], v[74:77]
	s_setprio 0
	s_setprio 1
	v_mfma_f32_16x16x32_bf16 v[118:121], v[168:171], v[184:187], 0
	v_mfma_f32_16x16x32_bf16 v[114:117], v[176:179], v[184:187], 0
	v_mfma_f32_16x16x32_bf16 v[102:105], v[168:171], v[192:195], 0
	v_mfma_f32_16x16x32_bf16 v[98:101], v[176:179], v[192:195], 0
	v_mfma_f32_16x16x32_bf16 v[86:89], v[168:171], v[200:203], 0
	v_mfma_f32_16x16x32_bf16 v[82:85], v[176:179], v[200:203], 0
	v_mfma_f32_16x16x32_bf16 v[70:73], v[168:171], v[208:211], 0
	v_mfma_f32_16x16x32_bf16 v[66:69], v[176:179], v[208:211], 0
	v_mfma_f32_16x16x32_bf16 v[118:121], v[172:175], v[188:191], v[118:121]
	v_mfma_f32_16x16x32_bf16 v[114:117], v[180:183], v[188:191], v[114:117]
	v_mfma_f32_16x16x32_bf16 v[102:105], v[172:175], v[196:199], v[102:105]
	v_mfma_f32_16x16x32_bf16 v[98:101], v[180:183], v[196:199], v[98:101]
	v_mfma_f32_16x16x32_bf16 v[86:89], v[172:175], v[204:207], v[86:89]
	v_mfma_f32_16x16x32_bf16 v[82:85], v[180:183], v[204:207], v[82:85]
	v_mfma_f32_16x16x32_bf16 v[70:73], v[172:175], v[212:215], v[70:73]
	v_mfma_f32_16x16x32_bf16 v[66:69], v[180:183], v[212:215], v[66:69]
	s_setprio 0
	s_barrier
	s_add_i32 s3, s33, s12
	v_lshl_add_u64 v[216:217], s[42:43], 0, v[134:135]
	s_mov_b32 m0, s3
	ds_read_b128 v[184:187], v150 offset:16384
	ds_read_b128 v[188:191], v150 offset:17408
	ds_read_b128 v[192:195], v150 offset:18432
	ds_read_b128 v[196:199], v150 offset:19456
	ds_read_b128 v[200:203], v150 offset:20480
	ds_read_b128 v[204:207], v150 offset:21504
	ds_read_b128 v[208:211], v150 offset:22528
	ds_read_b128 v[212:215], v150 offset:23552
	global_load_lds_dwordx4 v[216:217], off
	s_add_i32 m0, s3, 0x2000
	s_add_u32 s56, s42, 0x40000
	v_lshl_add_u64 v[218:219], s[42:43], 0, v[130:131]
	s_addc_u32 s57, s43, 0
	s_add_i32 s3, s50, s12
	global_load_lds_dwordx4 v[218:219], off
	v_lshl_add_u64 v[220:221], s[56:57], 0, v[134:135]
	s_mov_b32 m0, s3
	v_lshl_add_u64 v[222:223], s[44:45], 0, v[132:133]
	global_load_lds_dwordx4 v[220:221], off
	v_lshl_add_u64 v[220:221], s[56:57], 0, v[130:131]
	s_add_i32 m0, s3, 0x2000
	s_nop 0
	global_load_lds_dwordx4 v[220:221], off
	v_lshl_add_u64 v[220:221], s[44:45], 0, v[136:137]
	s_mov_b32 m0, s35
	s_nop 0
	global_load_lds_dwordx4 v[220:221], off
	s_mov_b32 m0, s39
	s_nop 0
	global_load_lds_dwordx4 v[222:223], off
	s_waitcnt vmcnt(8)
	s_waitcnt lgkmcnt(0)
	s_barrier
; #define PG8_STAGE(bufoff, gbase, voff) do { _Pragma("unroll") for (int _i = 0; _i < 2; ++_i) \
;         __builtin_amdgcn_global_load_lds((const unsigned*)((const char*)(gbase) + (voff)[_i]), (PG8_LAS unsigned*)(lds + (bufoff) + ldsw + _i * 8192), 16, 0, 0); } while (0)
; #define PG8_LDA(dst, b, h) do { _Pragma("unroll") for (int m = 0; m < 4; ++m) _Pragma("unroll") for (int k = 0; k < 2; ++k) dst[m][k] = *(const PG8_LAS bf16x8*)(lds + PG8_SA(b, h) + aoff + m * 2048 + k * 1024); } while (0)
; #define PG8_LDB(dst, b, h) do { _Pragma("unroll") for (int n = 0; n < 2; ++n) _Pragma("unroll") for (int k = 0; k < 2; ++k) dst[n][k] = *(const PG8_LAS bf16x8*)(lds + PG8_SB(b, h) + boff + n * 2048 + k * 1024); } while (0)
; #define PG8_MMA(ai, bj, At, Bt) do { __builtin_amdgcn_s_setprio(1); _Pragma("unroll") for (int m = 0; m < 4; ++m) _Pragma("unroll") for (int n = 0; n < 2; ++n) _Pragma("unroll") for (int k = 0; k < 2; ++k) \
;         acc[ai][bj][m][n] = __builtin_amdgcn_mfma_f32_16x16x32_bf16(Bt[n][k], At[m][k], acc[ai][bj][m][n], 0, 0, 0); __builtin_amdgcn_s_setprio(0); } while (0)
; #define PG8_WAIT_V(n) asm volatile("s_waitcnt vmcnt(" #n ")" ::: "memory")
; #define PG8_WAIT_L(n) asm volatile("s_waitcnt lgkmcnt(" #n ")" ::: "memory")
; #define PG8_BAR __builtin_amdgcn_s_barrier()
; #define PG8_SCHED __builtin_amdgcn_sched_barrier(0)
; template <class Epi, class Sched, bool ALIGN_EPI = false, bool SP2 = false>
; __device__ __forceinline__ void gemm_phase(PG8_LAS unsigned char* lds, const Gemm g, const Sched& S, const Epi& E) {
;     ...
;             PG8_WAIT_V(8); PG8_WAIT_L(0); PG8_BAR; PG8_MMA(1, 0, At, B0); PG8_MMA(1, 1, At, B1); PG8_BAR; PG8_SCHED;
;             PG8_LDB(B0, 1, 0); PG8_LDB(B1, 1, 1); PG8_SCHED; PG8_LDA(At, 1, 0); PG8_STAGE(PG8_SA(0, 1), a2 + hstep, voffA);
;             PG8_WAIT_V(8); PG8_WAIT_L(0); PG8_BAR; PG8_MMA(0, 0, At, B0); PG8_MMA(0, 1, At, B1); PG8_BAR; PG8_SCHED;
	s_setprio 1
	s_waitcnt lgkmcnt(0)
	v_mfma_f32_16x16x32_bf16 v[62:65], v[152:155], v[184:187], 0
	v_mfma_f32_16x16x32_bf16 v[58:61], v[160:163], v[184:187], 0
	v_mfma_f32_16x16x32_bf16 v[46:49], v[152:155], v[192:195], 0
	v_mfma_f32_16x16x32_bf16 v[42:45], v[160:163], v[192:195], 0
	v_mfma_f32_16x16x32_bf16 v[30:33], v[152:155], v[200:203], 0
	v_mfma_f32_16x16x32_bf16 v[26:29], v[160:163], v[200:203], 0
	v_mfma_f32_16x16x32_bf16 v[14:17], v[152:155], v[208:211], 0
	v_mfma_f32_16x16x32_bf16 v[10:13], v[160:163], v[208:211], 0
	v_mfma_f32_16x16x32_bf16 v[62:65], v[156:159], v[188:191], v[62:65]
	v_mfma_f32_16x16x32_bf16 v[58:61], v[164:167], v[188:191], v[58:61]
	v_mfma_f32_16x16x32_bf16 v[46:49], v[156:159], v[196:199], v[46:49]
	v_mfma_f32_16x16x32_bf16 v[42:45], v[164:167], v[196:199], v[42:45]
	v_mfma_f32_16x16x32_bf16 v[30:33], v[156:159], v[204:207], v[30:33]
	v_mfma_f32_16x16x32_bf16 v[26:29], v[164:167], v[204:207], v[26:29]
	v_mfma_f32_16x16x32_bf16 v[14:17], v[156:159], v[212:215], v[14:17]
	v_mfma_f32_16x16x32_bf16 v[10:13], v[164:167], v[212:215], v[10:13]
	s_setprio 0
	s_setprio 1
	v_mfma_f32_16x16x32_bf16 v[54:57], v[168:171], v[184:187], 0
	v_mfma_f32_16x16x32_bf16 v[50:53], v[176:179], v[184:187], 0
	v_mfma_f32_16x16x32_bf16 v[38:41], v[168:171], v[192:195], 0
	v_mfma_f32_16x16x32_bf16 v[34:37], v[176:179], v[192:195], 0
	v_mfma_f32_16x16x32_bf16 v[22:25], v[168:171], v[200:203], 0
	v_mfma_f32_16x16x32_bf16 v[18:21], v[176:179], v[200:203], 0
	v_mfma_f32_16x16x32_bf16 v[6:9], v[168:171], v[208:211], 0
	v_mfma_f32_16x16x32_bf16 v[2:5], v[176:179], v[208:211], 0
	v_mfma_f32_16x16x32_bf16 v[54:57], v[172:175], v[188:191], v[54:57]
	v_mfma_f32_16x16x32_bf16 v[50:53], v[180:183], v[188:191], v[50:53]
	v_mfma_f32_16x16x32_bf16 v[38:41], v[172:175], v[196:199], v[38:41]
	v_mfma_f32_16x16x32_bf16 v[34:37], v[180:183], v[196:199], v[34:37]
	v_mfma_f32_16x16x32_bf16 v[22:25], v[172:175], v[204:207], v[22:25]
	v_mfma_f32_16x16x32_bf16 v[18:21], v[180:183], v[204:207], v[18:21]
	v_mfma_f32_16x16x32_bf16 v[6:9], v[172:175], v[212:215], v[6:9]
	v_mfma_f32_16x16x32_bf16 v[2:5], v[180:183], v[212:215], v[2:5]
	s_setprio 0
	s_barrier
	s_add_i32 s3, 0, 0x18000
	v_add_u32_e32 v151, s3, v146
	s_add_i32 s56, 0, 0x1c000
	ds_read_b128 v[152:155], v151
	ds_read_b128 v[156:159], v151 offset:1024
	ds_read_b128 v[160:163], v151 offset:2048
	ds_read_b128 v[164:167], v151 offset:3072
	v_add_u32_e32 v151, s56, v146
	ds_read_b128 v[168:171], v151
	ds_read_b128 v[172:175], v151 offset:1024
	ds_read_b128 v[176:179], v151 offset:2048
	ds_read_b128 v[180:183], v151 offset:3072
	s_add_u32 s44, s44, 0x40000
	s_addc_u32 s45, s45, 0
	s_mov_b32 m0, s46
	v_lshl_add_u64 v[224:225], s[44:45], 0, v[136:137]
	ds_read_b128 v[184:187], v150 offset:32768
	ds_read_b128 v[188:191], v150 offset:33792
	ds_read_b128 v[192:195], v150 offset:34816
	ds_read_b128 v[196:199], v150 offset:35840
	ds_read_b128 v[200:203], v150 offset:36864
	ds_read_b128 v[204:207], v150 offset:37888
	ds_read_b128 v[208:211], v150 offset:38912
	ds_read_b128 v[212:215], v150 offset:39936
	global_load_lds_dwordx4 v[224:225], off
	v_lshl_add_u64 v[224:225], s[44:45], 0, v[132:133]
	s_mov_b32 m0, s47
	s_nop 0
	global_load_lds_dwordx4 v[224:225], off
	s_waitcnt vmcnt(8)
	s_waitcnt lgkmcnt(0)
	s_barrier
	s_setprio 1
	s_waitcnt lgkmcnt(0)
	v_mfma_f32_16x16x32_bf16 v[126:129], v[152:155], v[184:187], v[126:129]
	v_mfma_f32_16x16x32_bf16 v[122:125], v[160:163], v[184:187], v[122:125]
	v_mfma_f32_16x16x32_bf16 v[110:113], v[152:155], v[192:195], v[110:113]
	v_mfma_f32_16x16x32_bf16 v[106:109], v[160:163], v[192:195], v[106:109]
	v_mfma_f32_16x16x32_bf16 v[94:97], v[152:155], v[200:203], v[94:97]
	v_mfma_f32_16x16x32_bf16 v[90:93], v[160:163], v[200:203], v[90:93]
	v_mfma_f32_16x16x32_bf16 v[78:81], v[152:155], v[208:211], v[78:81]
	v_mfma_f32_16x16x32_bf16 v[74:77], v[160:163], v[208:211], v[74:77]
	v_mfma_f32_16x16x32_bf16 v[126:129], v[156:159], v[188:191], v[126:129]
	v_mfma_f32_16x16x32_bf16 v[122:125], v[164:167], v[188:191], v[122:125]
	v_mfma_f32_16x16x32_bf16 v[110:113], v[156:159], v[196:199], v[110:113]
	v_mfma_f32_16x16x32_bf16 v[106:109], v[164:167], v[196:199], v[106:109]
	v_mfma_f32_16x16x32_bf16 v[94:97], v[156:159], v[204:207], v[94:97]
	v_mfma_f32_16x16x32_bf16 v[90:93], v[164:167], v[204:207], v[90:93]
	v_mfma_f32_16x16x32_bf16 v[78:81], v[156:159], v[212:215], v[78:81]
	v_mfma_f32_16x16x32_bf16 v[74:77], v[164:167], v[212:215], v[74:77]
	s_setprio 0
	s_setprio 1
	v_mfma_f32_16x16x32_bf16 v[118:121], v[168:171], v[184:187], v[118:121]
	v_mfma_f32_16x16x32_bf16 v[114:117], v[176:179], v[184:187], v[114:117]
	v_mfma_f32_16x16x32_bf16 v[102:105], v[168:171], v[192:195], v[102:105]
	v_mfma_f32_16x16x32_bf16 v[98:101], v[176:179], v[192:195], v[98:101]
	v_mfma_f32_16x16x32_bf16 v[86:89], v[168:171], v[200:203], v[86:89]
	v_mfma_f32_16x16x32_bf16 v[82:85], v[176:179], v[200:203], v[82:85]
	v_mfma_f32_16x16x32_bf16 v[70:73], v[168:171], v[208:211], v[70:73]
	v_mfma_f32_16x16x32_bf16 v[66:69], v[176:179], v[208:211], v[66:69]
	v_mfma_f32_16x16x32_bf16 v[118:121], v[172:175], v[188:191], v[118:121]
	v_mfma_f32_16x16x32_bf16 v[114:117], v[180:183], v[188:191], v[114:117]
	v_mfma_f32_16x16x32_bf16 v[102:105], v[172:175], v[196:199], v[102:105]
	v_mfma_f32_16x16x32_bf16 v[98:101], v[180:183], v[196:199], v[98:101]
	v_mfma_f32_16x16x32_bf16 v[86:89], v[172:175], v[204:207], v[86:89]
	v_mfma_f32_16x16x32_bf16 v[82:85], v[180:183], v[204:207], v[82:85]
	v_mfma_f32_16x16x32_bf16 v[70:73], v[172:175], v[212:215], v[70:73]
	v_mfma_f32_16x16x32_bf16 v[66:69], v[180:183], v[212:215], v[66:69]
	s_setprio 0
	s_barrier
; #define PG8_STAGE(bufoff, gbase, voff) do { _Pragma("unroll") for (int _i = 0; _i < 2; ++_i) \
;         __builtin_amdgcn_global_load_lds((const unsigned*)((const char*)(gbase) + (voff)[_i]), (PG8_LAS unsigned*)(lds + (bufoff) + ldsw + _i * 8192), 16, 0, 0); } while (0)
; #define PG8_LDA(dst, b, h) do { _Pragma("unroll") for (int m = 0; m < 4; ++m) _Pragma("unroll") for (int k = 0; k < 2; ++k) dst[m][k] = *(const PG8_LAS bf16x8*)(lds + PG8_SA(b, h) + aoff + m * 2048 + k * 1024); } while (0)
; #define PG8_MMA(ai, bj, At, Bt) do { __builtin_amdgcn_s_setprio(1); _Pragma("unroll") for (int m = 0; m < 4; ++m) _Pragma("unroll") for (int n = 0; n < 2; ++n) _Pragma("unroll") for (int k = 0; k < 2; ++k) \
;         acc[ai][bj][m][n] = __builtin_amdgcn_mfma_f32_16x16x32_bf16(Bt[n][k], At[m][k], acc[ai][bj][m][n], 0, 0, 0); __builtin_amdgcn_s_setprio(0); } while (0)
; #define PG8_WAIT_V(n) asm volatile("s_waitcnt vmcnt(" #n ")" ::: "memory")
; #define PG8_WAIT_L(n) asm volatile("s_waitcnt lgkmcnt(" #n ")" ::: "memory")
; #define PG8_BAR __builtin_amdgcn_s_barrier()
; #define PG8_SCHED __builtin_amdgcn_sched_barrier(0)
; template <class Epi, class Sched, bool ALIGN_EPI = false, bool SP2 = false>
; __device__ __forceinline__ void gemm_phase(PG8_LAS unsigned char* lds, const Gemm g, const Sched& S, const Epi& E) {
;     ...
;             PG8_LDA(At, 1, 1); PG8_STAGE(PG8_SB(1, 0), b3, voffB); PG8_STAGE(PG8_SB(1, 1), b3 + hstep, voffB); PG8_STAGE(PG8_SA(1, 0), a3, voffA);
;             PG8_WAIT_V(8); PG8_WAIT_L(0); PG8_BAR; PG8_MMA(1, 0, At, B0); PG8_MMA(1, 1, At, B1); PG8_BAR; PG8_SCHED;
	s_add_i32 s3, s3, s12
	v_lshl_add_u64 v[216:217], v[216:217], 0, s[14:15]
	s_mov_b32 m0, s3
	ds_read_b128 v[184:187], v150 offset:49152
	ds_read_b128 v[188:191], v150 offset:50176
	ds_read_b128 v[192:195], v150 offset:51200
	ds_read_b128 v[196:199], v150 offset:52224
	ds_read_b128 v[200:203], v150 offset:53248
	ds_read_b128 v[204:207], v150 offset:54272
	ds_read_b128 v[208:211], v150 offset:55296
	ds_read_b128 v[212:215], v150 offset:56320
	global_load_lds_dwordx4 v[216:217], off
	s_add_i32 m0, s3, 0x2000
	s_add_u32 s42, s42, 0x40080
	v_lshl_add_u64 v[216:217], v[218:219], 0, s[14:15]
	s_addc_u32 s43, s43, 0
	s_add_i32 s3, s56, s12
	global_load_lds_dwordx4 v[216:217], off
	v_lshl_add_u64 v[216:217], s[42:43], 0, v[134:135]
	s_mov_b32 m0, s3
	s_nop 0
	global_load_lds_dwordx4 v[216:217], off
	v_lshl_add_u64 v[216:217], s[42:43], 0, v[130:131]
	s_add_i32 m0, s3, 0x2000
	s_nop 0
	global_load_lds_dwordx4 v[216:217], off
	v_lshl_add_u64 v[216:217], v[220:221], 0, s[14:15]
	s_mov_b32 m0, s48
	s_nop 0
	global_load_lds_dwordx4 v[216:217], off
	v_lshl_add_u64 v[216:217], v[222:223], 0, s[14:15]
	s_mov_b32 m0, s49
	s_nop 0
	global_load_lds_dwordx4 v[216:217], off
	s_waitcnt vmcnt(8)
	s_waitcnt lgkmcnt(0)
	s_barrier
	s_setprio 1
	s_waitcnt lgkmcnt(0)
	v_mfma_f32_16x16x32_bf16 v[62:65], v[152:155], v[184:187], v[62:65]
	s_add_i32 s55, s55, 2
	s_add_u32 s40, s40, 0x100
	s_addc_u32 s41, s41, 0
	s_add_u32 s53, s53, 0x100
	s_addc_u32 s54, s54, 0
	s_cmp_gt_u32 s55, 13
	v_mfma_f32_16x16x32_bf16 v[58:61], v[160:163], v[184:187], v[58:61]
	v_mfma_f32_16x16x32_bf16 v[46:49], v[152:155], v[192:195], v[46:49]
	v_mfma_f32_16x16x32_bf16 v[42:45], v[160:163], v[192:195], v[42:45]
	v_mfma_f32_16x16x32_bf16 v[30:33], v[152:155], v[200:203], v[30:33]
	v_mfma_f32_16x16x32_bf16 v[26:29], v[160:163], v[200:203], v[26:29]
	v_mfma_f32_16x16x32_bf16 v[14:17], v[152:155], v[208:211], v[14:17]
	v_mfma_f32_16x16x32_bf16 v[10:13], v[160:163], v[208:211], v[10:13]
	v_mfma_f32_16x16x32_bf16 v[62:65], v[156:159], v[188:191], v[62:65]
	v_mfma_f32_16x16x32_bf16 v[58:61], v[164:167], v[188:191], v[58:61]
	v_mfma_f32_16x16x32_bf16 v[46:49], v[156:159], v[196:199], v[46:49]
	v_mfma_f32_16x16x32_bf16 v[42:45], v[164:167], v[196:199], v[42:45]
	v_mfma_f32_16x16x32_bf16 v[30:33], v[156:159], v[204:207], v[30:33]
	v_mfma_f32_16x16x32_bf16 v[26:29], v[164:167], v[204:207], v[26:29]
	v_mfma_f32_16x16x32_bf16 v[14:17], v[156:159], v[212:215], v[14:17]
	v_mfma_f32_16x16x32_bf16 v[10:13], v[164:167], v[212:215], v[10:13]
	s_setprio 0
	s_setprio 1
	v_mfma_f32_16x16x32_bf16 v[54:57], v[168:171], v[184:187], v[54:57]
	v_mfma_f32_16x16x32_bf16 v[50:53], v[176:179], v[184:187], v[50:53]
	v_mfma_f32_16x16x32_bf16 v[38:41], v[168:171], v[192:195], v[38:41]
	v_mfma_f32_16x16x32_bf16 v[34:37], v[176:179], v[192:195], v[34:37]
	v_mfma_f32_16x16x32_bf16 v[22:25], v[168:171], v[200:203], v[22:25]
	v_mfma_f32_16x16x32_bf16 v[18:21], v[176:179], v[200:203], v[18:21]
	v_mfma_f32_16x16x32_bf16 v[6:9], v[168:171], v[208:211], v[6:9]
	v_mfma_f32_16x16x32_bf16 v[2:5], v[176:179], v[208:211], v[2:5]
	v_mfma_f32_16x16x32_bf16 v[54:57], v[172:175], v[188:191], v[54:57]
	v_mfma_f32_16x16x32_bf16 v[50:53], v[180:183], v[188:191], v[50:53]
	v_mfma_f32_16x16x32_bf16 v[38:41], v[172:175], v[196:199], v[38:41]
	v_mfma_f32_16x16x32_bf16 v[34:37], v[180:183], v[196:199], v[34:37]
	v_mfma_f32_16x16x32_bf16 v[22:25], v[172:175], v[204:207], v[22:25]
	v_mfma_f32_16x16x32_bf16 v[18:21], v[180:183], v[204:207], v[18:21]
	v_mfma_f32_16x16x32_bf16 v[6:9], v[172:175], v[212:215], v[6:9]
	v_mfma_f32_16x16x32_bf16 v[2:5], v[180:183], v[212:215], v[2:5]
	s_setprio 0
	s_barrier
